# deferred-max loop: next-tile LDS stage store issued at the start of the softmax segment instead of before the barrier
# speedup vs baseline: 1.0025x; 1.0025x over previous
; #define LAS __attribute__((address_space(3)))
; __device__ __forceinline__ u32x4 pack8(const f32x4 a, const f32x4 b) { u32x4 w; w.x = cvt_pk_bf16(a[0], a[1]); w.y = cvt_pk_bf16(a[2], a[3]); w.z = cvt_pk_bf16(b[0], b[1]); w.w = cvt_pk_bf16(b[2], b[3]); return w; }
; __device__ __forceinline__ void pv_tile2(f32x4 (&o)[2][8], const u32x4 (&pk)[2][2], const LAS unsigned char* buf, int ql, int g) {
; #pragma unroll
;     for (int ch = 0; ch < 2; ++ch) {
;         const bf16x8 pf0 = __builtin_bit_cast(bf16x8, pk[0][ch]), pf1 = __builtin_bit_cast(bf16x8, pk[1][ch]);
; #pragma unroll
;         for (int dt = 0; dt < 8; ++dt) {
;             const LAS unsigned char* rowp = buf + KB_BYTES + (16 * dt + ql) * VT_PITCH + (32 * ch + 4 * g) * 2;
;             const u32x2 lo = *(const LAS u32x2*)(rowp), hi = *(const LAS u32x2*)(rowp + 32);
;             const bf16x8 vf = __builtin_bit_cast(bf16x8, (u32x4){lo.x, lo.y, hi.x, hi.y});
;             o[0][dt] = __builtin_amdgcn_mfma_f32_16x16x32_bf16(vf, pf0, o[0][dt], 0, 0, 0);
;             o[1][dt] = __builtin_amdgcn_mfma_f32_16x16x32_bf16(vf, pf1, o[1][dt], 0, 0, 0);
;             if ((dt & 3) == 3) asm volatile("" ::: "memory");
;         }
;     }
; }
; template <int MODE, bool DEFER> ...
;     ...
; #pragma unroll
;         for (int gp = 0; gp < 2; ++gp) {
;             float ps = 0.f;
; #pragma unroll
;             for (int sub = 0; sub < 4; ++sub)
; #pragma unroll
;                 for (int e = 0; e < 4; ++e) { const float pv = __builtin_amdgcn_exp2f(s[gp][sub][e]); s[gp][sub][e] = pv; ps += pv; }
;             lsum[gp] += ps;
;             pk[gp][0] = pack8(s[gp][0], s[gp][1]); pk[gp][1] = pack8(s[gp][2], s[gp][3]);
;         }
;     } else {
; #pragma unroll
;         for (int gp = 0; gp < 2; ++gp) {
;             int rel, lowrel = -1000000;
;             if (MODE == 0) rel = ((t[gp] - 31) >> 4) - tile * 64 - 4 * g;
;             else { rel = t[gp] - tile * 64 - 4 * g; if (MODE == 2) lowrel = rel - 512; }
;             softmax_tile<false>(s[gp], o[gp], pk[gp], mrun[gp], lsum[gp], take[gp], rel, lowrel);
;         }
;     }
;     pv_tile2(o, pk, buf, ql, g);
;     if (tile < tile_hi) stage_store<true, true>(R, lds + ((tile + 1) & 1) * BUF_BYTES, tid);
;     __syncthreads();
.LBB0_1007:
	s_andn2_b32 s15, 1, s1
	s_mul_i32 s15, s15, 0x8c00
	v_add_u32_e32 v180, s15, v205
	v_add_u32_e32 v181, s15, v206
	v_add_u32_e32 v182, v180, v207
	v_add_u32_e32 v183, v181, v208
	v_add_u32_e32 v180, v180, v209
	v_add_u32_e32 v181, v181, v210
	s_waitcnt vmcnt(2)
	ds_write_b128 v182, v[36:39]
	s_waitcnt vmcnt(1)
	ds_write_b128 v183, v[40:43] offset:17408
	ds_write_b128 v180, v[44:47]
	s_waitcnt vmcnt(0)
	ds_write_b128 v181, v[48:51] offset:17408
	v_add3_u32 v3, s11, v148, v204
	v_exp_f32_e32 v181, v144
	v_exp_f32_e32 v180, v128
	v_exp_f32_e32 v145, v145
	v_exp_f32_e32 v144, v129
	v_exp_f32_e32 v183, v146
	v_exp_f32_e32 v182, v130
	v_exp_f32_e32 v147, v147
	v_exp_f32_e32 v146, v131
	v_exp_f32_e32 v185, v140
	v_exp_f32_e32 v184, v124
	v_exp_f32_e32 v188, v120
	v_exp_f32_e32 v190, v121
	v_pk_add_f32 v[120:121], v[180:181], 0 op_sel_hi:[1,0]
	v_exp_f32_e32 v141, v141
	v_exp_f32_e32 v140, v125
	v_pk_add_f32 v[120:121], v[144:145], v[120:121]
	v_exp_f32_e32 v187, v142
	v_exp_f32_e32 v186, v126
	v_pk_add_f32 v[120:121], v[182:183], v[120:121]
	v_exp_f32_e32 v143, v143
	v_exp_f32_e32 v142, v127
	ds_read_b64 v[124:125], v3 offset:17408
	ds_read_b64 v[126:127], v3 offset:17440
	v_pk_add_f32 v[120:121], v[146:147], v[120:121]
	v_exp_f32_e32 v189, v136
	v_pk_add_f32 v[120:121], v[184:185], v[120:121]
	v_exp_f32_e32 v191, v137
	v_pk_add_f32 v[120:121], v[140:141], v[120:121]
	v_exp_f32_e32 v193, v138
	v_pk_add_f32 v[120:121], v[186:187], v[120:121]
	v_exp_f32_e32 v192, v122
	v_exp_f32_e32 v197, v139
	v_pk_add_f32 v[120:121], v[142:143], v[120:121]
	v_exp_f32_e32 v196, v123
	v_exp_f32_e32 v199, v132
	v_pk_add_f32 v[120:121], v[188:189], v[120:121]
	v_exp_f32_e32 v198, v116
	v_exp_f32_e32 v203, v133
	v_pk_add_f32 v[120:121], v[190:191], v[120:121]
	v_exp_f32_e32 v202, v117
	v_exp_f32_e32 v213, v134
	v_exp_f32_e32 v212, v118
	v_pk_add_f32 v[116:117], v[192:193], v[120:121]
	v_exp_f32_e32 v215, v135
	v_exp_f32_e32 v214, v119
	v_pk_add_f32 v[116:117], v[196:197], v[116:117]
	v_pk_add_f32 v[116:117], v[198:199], v[116:117]
	v_pk_add_f32 v[116:117], v[202:203], v[116:117]
	v_cvt_pk_bf16_f32 v136, v181, v145
	v_cvt_pk_bf16_f32 v137, v183, v147
	v_cvt_pk_bf16_f32 v138, v185, v141
	v_cvt_pk_bf16_f32 v139, v187, v143
	v_cvt_pk_bf16_f32 v132, v189, v191
	s_nop 0
	v_pk_add_f32 v[116:117], v[212:213], v[116:117]
	v_cvt_pk_bf16_f32 v133, v193, v197
	v_cvt_pk_bf16_f32 v134, v199, v203
	v_cvt_pk_bf16_f32 v135, v213, v215
	v_cvt_pk_bf16_f32 v120, v180, v144
	v_cvt_pk_bf16_f32 v121, v182, v146
	s_nop 0
	v_pk_add_f32 v[116:117], v[214:215], v[116:117]
	v_cvt_pk_bf16_f32 v122, v184, v140
	v_cvt_pk_bf16_f32 v123, v186, v142
	v_pk_add_f32 v[168:169], v[168:169], v[116:117]
	v_cvt_pk_bf16_f32 v116, v188, v190
	v_cvt_pk_bf16_f32 v117, v192, v196
	v_cvt_pk_bf16_f32 v118, v198, v202
	v_cvt_pk_bf16_f32 v119, v212, v214
	ds_read_b64 v[144:145], v3 offset:19712
	ds_read_b64 v[146:147], v3 offset:19744
	ds_read_b64 v[180:181], v3 offset:22016
	ds_read_b64 v[182:183], v3 offset:22048
	ds_read_b64 v[184:185], v3 offset:24320
	ds_read_b64 v[186:187], v3 offset:24352
	ds_read_b64 v[188:189], v3 offset:26624
	ds_read_b64 v[190:191], v3 offset:26656
	ds_read_b64 v[196:197], v3 offset:28928
	ds_read_b64 v[198:199], v3 offset:28960
	ds_read_b64 v[212:213], v3 offset:31232
	ds_read_b64 v[214:215], v3 offset:31264
	s_andn2_b32 s7, 1, s1
	s_mul_i32 s7, s7, 0x8c00
	s_add_i32 s7, s7, 0
	s_add_u32 s1, s1, 1
	s_addc_u32 s10, s10, 0
	s_add_i32 s6, s6, 64
	s_cmp_ge_i32 s1, s0
	s_waitcnt lgkmcnt(12)
	v_mfma_f32_16x16x32_bf16 v[104:107], v[124:127], v[136:139], v[104:107]
	v_mfma_f32_16x16x32_bf16 v[80:83], v[124:127], v[120:123], v[80:83]
	ds_read_b64 v[140:141], v3 offset:33536
	ds_read_b64 v[142:143], v3 offset:33568
	s_waitcnt lgkmcnt(12)
	v_mfma_f32_16x16x32_bf16 v[108:111], v[144:147], v[136:139], v[108:111]
	v_mfma_f32_16x16x32_bf16 v[76:79], v[144:147], v[120:123], v[76:79]
	ds_read_b64 v[124:125], v3 offset:17472
	ds_read_b64 v[126:127], v3 offset:17504
	s_waitcnt lgkmcnt(12)
	v_mfma_f32_16x16x32_bf16 v[100:103], v[180:183], v[136:139], v[100:103]
	v_mfma_f32_16x16x32_bf16 v[72:75], v[180:183], v[120:123], v[72:75]
	ds_read_b64 v[144:145], v3 offset:19776
	ds_read_b64 v[146:147], v3 offset:19808
	s_waitcnt lgkmcnt(12)
	v_mfma_f32_16x16x32_bf16 v[96:99], v[184:187], v[136:139], v[96:99]
	v_mfma_f32_16x16x32_bf16 v[68:71], v[184:187], v[120:123], v[68:71]
	ds_read_b64 v[180:181], v3 offset:22080
	ds_read_b64 v[182:183], v3 offset:22112
	s_waitcnt lgkmcnt(12)
	v_mfma_f32_16x16x32_bf16 v[88:91], v[188:191], v[136:139], v[88:91]
	v_mfma_f32_16x16x32_bf16 v[60:63], v[188:191], v[120:123], v[60:63]
	ds_read_b64 v[184:185], v3 offset:24384
	ds_read_b64 v[186:187], v3 offset:24416
	s_waitcnt lgkmcnt(12)
	v_mfma_f32_16x16x32_bf16 v[84:87], v[196:199], v[136:139], v[84:87]
	v_mfma_f32_16x16x32_bf16 v[52:55], v[196:199], v[120:123], v[52:55]
	ds_read_b64 v[188:189], v3 offset:26688
	ds_read_b64 v[190:191], v3 offset:26720
	s_waitcnt lgkmcnt(12)
	v_mfma_f32_16x16x32_bf16 v[92:95], v[212:215], v[136:139], v[92:95]
	v_mfma_f32_16x16x32_bf16 v[64:67], v[212:215], v[120:123], v[64:67]
	ds_read_b64 v[196:197], v3 offset:28992
	ds_read_b64 v[198:199], v3 offset:29024
	s_waitcnt lgkmcnt(12)
	v_mfma_f32_16x16x32_bf16 v[112:115], v[140:143], v[136:139], v[112:115]
	v_mfma_f32_16x16x32_bf16 v[56:59], v[140:143], v[120:123], v[56:59]
	ds_read_b64 v[212:213], v3 offset:31296
	ds_read_b64 v[214:215], v3 offset:31328
	s_waitcnt lgkmcnt(12)
	v_mfma_f32_16x16x32_bf16 v[104:107], v[124:127], v[132:135], v[104:107]
	v_mfma_f32_16x16x32_bf16 v[80:83], v[124:127], v[116:119], v[80:83]
	ds_read_b64 v[140:141], v3 offset:33600
	ds_read_b64 v[142:143], v3 offset:33632
	s_waitcnt lgkmcnt(12)
	v_mfma_f32_16x16x32_bf16 v[108:111], v[144:147], v[132:135], v[108:111]
	v_mfma_f32_16x16x32_bf16 v[76:79], v[144:147], v[116:119], v[76:79]
	s_waitcnt lgkmcnt(10)
	v_mfma_f32_16x16x32_bf16 v[100:103], v[180:183], v[132:135], v[100:103]
	v_mfma_f32_16x16x32_bf16 v[72:75], v[180:183], v[116:119], v[72:75]
	s_waitcnt lgkmcnt(8)
	v_mfma_f32_16x16x32_bf16 v[96:99], v[184:187], v[132:135], v[96:99]
	v_mfma_f32_16x16x32_bf16 v[68:71], v[184:187], v[116:119], v[68:71]
	s_waitcnt lgkmcnt(6)
	v_mfma_f32_16x16x32_bf16 v[88:91], v[188:191], v[132:135], v[88:91]
	v_mfma_f32_16x16x32_bf16 v[60:63], v[188:191], v[116:119], v[60:63]
	s_waitcnt lgkmcnt(4)
	v_mfma_f32_16x16x32_bf16 v[84:87], v[196:199], v[132:135], v[84:87]
	v_mfma_f32_16x16x32_bf16 v[52:55], v[196:199], v[116:119], v[52:55]
	s_waitcnt lgkmcnt(2)
	v_mfma_f32_16x16x32_bf16 v[92:95], v[212:215], v[132:135], v[92:95]
	v_mfma_f32_16x16x32_bf16 v[64:67], v[212:215], v[116:119], v[64:67]
	s_waitcnt lgkmcnt(0)
	v_mfma_f32_16x16x32_bf16 v[112:115], v[140:143], v[132:135], v[112:115]
	v_mfma_f32_16x16x32_bf16 v[56:59], v[140:143], v[116:119], v[56:59]
	s_waitcnt lgkmcnt(0)
	s_barrier
	s_cbranch_scc1 .LBB0_1010
